# phase0: the four MLP weight conversions move their 64x64 tiles global->LDS by LDS-DMA into three padded transpose buffers (two tiles in flight, one barrier per tile) instead of one register-staged til
# speedup vs baseline: 1.0070x; 1.0070x over previous
.LBB0_85:
	s_mul_hi_u32 s6, s35, 0x1080
	s_add_u32 s58, s84, 0x988000
	s_mul_i32 s6, s6, s3
	s_addc_u32 s59, s85, 0
	s_sub_i32 s6, 0x1080, s6
	s_sub_i32 s7, s6, s3
	s_cmp_ge_u32 s6, s3
	s_cselect_b32 s6, s7, s6
	s_sub_i32 s7, s6, s3
	s_cmp_ge_u32 s6, s3
	s_cselect_b32 s6, s7, s6
	s_sub_i32 s6, s34, s6
	s_ashr_i32 s7, s6, 31
	s_abs_i32 s6, s6
	s_mul_hi_u32 s8, s6, s35
	s_mul_i32 s8, s8, s3
	s_sub_i32 s6, s6, s8
	s_sub_i32 s8, s6, s3
	s_cmp_ge_u32 s6, s3
	s_cselect_b32 s6, s8, s6
	s_sub_i32 s8, s6, s3
	s_cmp_ge_u32 s6, s3
	s_cselect_b32 s6, s8, s6
	s_xor_b32 s6, s6, s7
	s_sub_i32 s10, s6, s7
	v_mov_b32_e32 v14, v174
	s_cmpk_gt_i32 s10, 0x3ff
	s_cbranch_scc1 .LBB0_92
	s_cmpk_lg_i32 s86, 0x100
	s_cbranch_scc1 .Lcv0_orig
	s_load_dwordx2 s[6:7], s[0:1], 0x60
	v_lshrrev_b32_e32 v2, 6, v174
	v_and_b32_e32 v1, 63, v174
	v_lshrrev_b32_e32 v6, 3, v174
	v_readfirstlane_b32 s8, v2
	v_and_b32_e32 v7, 7, v174
	s_mul_i32 s9, s8, 0x4000
	v_lshlrev_b32_e32 v18, 2, v1
	v_add_u32_e32 v18, s9, v18
	s_mul_i32 s11, s8, 260
	v_mul_u32_u24_e32 v8, 0x820, v7
	v_lshl_add_u32 v8, v6, 2, v8
	v_mov_b32_e32 v9, 0x880
	v_mul_u32_u24_e32 v9, v9, v6
	v_lshl_add_u32 v9, v7, 4, v9
	s_add_u32 s12, s84, 0x988000
	s_addc_u32 s13, s85, 0
	s_mov_b32 s15, 0
	s_waitcnt lgkmcnt(0)
	v_mov_b32_e32 v19, 0
	v_lshl_add_u64 v[10:11], s[6:7], 0, v[18:19]
	s_mov_b32 s16, 0x20000
	s_mov_b32 s17, 0
	s_add_i32 s14, s10, 0x0
	s_lshr_b32 s9, s14, 6
	s_and_b32 vcc_lo, s14, 0x3f
	s_mul_i32 s14, s9, 0x100000
	s_lshl_b32 vcc_lo, vcc_lo, 8
	s_add_i32 s14, s14, vcc_lo
	v_lshl_add_u64 v[12:13], v[10:11], 0, s[14:15]
	s_add_i32 m0, s11, 0x0
	s_nop 0
	global_load_lds_dword v[12:13], off
	v_lshl_add_u64 v[12:13], v[12:13], 0, s[16:17]
	s_add_i32 m0, s11, 0x820
	s_nop 0
	global_load_lds_dword v[12:13], off
	v_lshl_add_u64 v[12:13], v[12:13], 0, s[16:17]
	s_add_i32 m0, s11, 0x1040
	s_nop 0
	global_load_lds_dword v[12:13], off
	v_lshl_add_u64 v[12:13], v[12:13], 0, s[16:17]
	s_add_i32 m0, s11, 0x1860
	s_nop 0
	global_load_lds_dword v[12:13], off
	v_lshl_add_u64 v[12:13], v[12:13], 0, s[16:17]
	s_add_i32 m0, s11, 0x2080
	s_nop 0
	global_load_lds_dword v[12:13], off
	v_lshl_add_u64 v[12:13], v[12:13], 0, s[16:17]
	s_add_i32 m0, s11, 0x28a0
	s_nop 0
	global_load_lds_dword v[12:13], off
	v_lshl_add_u64 v[12:13], v[12:13], 0, s[16:17]
	s_add_i32 m0, s11, 0x30c0
	s_nop 0
	global_load_lds_dword v[12:13], off
	v_lshl_add_u64 v[12:13], v[12:13], 0, s[16:17]
	s_add_i32 m0, s11, 0x38e0
	s_nop 0
	global_load_lds_dword v[12:13], off
	s_add_i32 s14, s10, 0x100
	s_lshr_b32 s9, s14, 6
	s_and_b32 vcc_lo, s14, 0x3f
	s_mul_i32 s14, s9, 0x100000
	s_lshl_b32 vcc_lo, vcc_lo, 8
	s_add_i32 s14, s14, vcc_lo
	v_lshl_add_u64 v[12:13], v[10:11], 0, s[14:15]
	s_add_i32 m0, s11, 0x4100
	s_nop 0
	global_load_lds_dword v[12:13], off
	v_lshl_add_u64 v[12:13], v[12:13], 0, s[16:17]
	s_add_i32 m0, s11, 0x4920
	s_nop 0
	global_load_lds_dword v[12:13], off
	v_lshl_add_u64 v[12:13], v[12:13], 0, s[16:17]
	s_add_i32 m0, s11, 0x5140
	s_nop 0
	global_load_lds_dword v[12:13], off
	v_lshl_add_u64 v[12:13], v[12:13], 0, s[16:17]
	s_add_i32 m0, s11, 0x5960
	s_nop 0
	global_load_lds_dword v[12:13], off
	v_lshl_add_u64 v[12:13], v[12:13], 0, s[16:17]
	s_add_i32 m0, s11, 0x6180
	s_nop 0
	global_load_lds_dword v[12:13], off
	v_lshl_add_u64 v[12:13], v[12:13], 0, s[16:17]
	s_add_i32 m0, s11, 0x69a0
	s_nop 0
	global_load_lds_dword v[12:13], off
	v_lshl_add_u64 v[12:13], v[12:13], 0, s[16:17]
	s_add_i32 m0, s11, 0x71c0
	s_nop 0
	global_load_lds_dword v[12:13], off
	v_lshl_add_u64 v[12:13], v[12:13], 0, s[16:17]
	s_add_i32 m0, s11, 0x79e0
	s_nop 0
	global_load_lds_dword v[12:13], off
	s_waitcnt vmcnt(8)
	s_barrier
	s_add_i32 s14, s10, 0x200
	s_lshr_b32 s9, s14, 6
	s_and_b32 vcc_lo, s14, 0x3f
	s_mul_i32 s14, s9, 0x100000
	s_lshl_b32 vcc_lo, vcc_lo, 8
	s_add_i32 s14, s14, vcc_lo
	v_lshl_add_u64 v[12:13], v[10:11], 0, s[14:15]
	s_add_i32 m0, s11, 0x8200
	s_nop 0
	global_load_lds_dword v[12:13], off
	v_lshl_add_u64 v[12:13], v[12:13], 0, s[16:17]
	s_add_i32 m0, s11, 0x8a20
	s_nop 0
	global_load_lds_dword v[12:13], off
	v_lshl_add_u64 v[12:13], v[12:13], 0, s[16:17]
	s_add_i32 m0, s11, 0x9240
	s_nop 0
	global_load_lds_dword v[12:13], off
	v_lshl_add_u64 v[12:13], v[12:13], 0, s[16:17]
	s_add_i32 m0, s11, 0x9a60
	s_nop 0
	global_load_lds_dword v[12:13], off
	v_lshl_add_u64 v[12:13], v[12:13], 0, s[16:17]
	s_add_i32 m0, s11, 0xa280
	s_nop 0
	global_load_lds_dword v[12:13], off
	v_lshl_add_u64 v[12:13], v[12:13], 0, s[16:17]
	s_add_i32 m0, s11, 0xaaa0
	s_nop 0
	global_load_lds_dword v[12:13], off
	v_lshl_add_u64 v[12:13], v[12:13], 0, s[16:17]
	s_add_i32 m0, s11, 0xb2c0
	s_nop 0
	global_load_lds_dword v[12:13], off
	v_lshl_add_u64 v[12:13], v[12:13], 0, s[16:17]
	s_add_i32 m0, s11, 0xbae0
	s_nop 0
	global_load_lds_dword v[12:13], off
	v_mov_b32_e32 v14, v8
	v_add_u32_e32 v15, 0x410, v14
	ds_read2_b32 v[20:21], v14 offset1:65
	ds_read2_b32 v[22:23], v14 offset0:130 offset1:195
	ds_read2_b32 v[24:25], v15 offset1:65
	ds_read2_b32 v[26:27], v15 offset0:130 offset1:195
	s_add_i32 s14, s10, 0x0
	s_lshr_b32 s9, s14, 6
	s_and_b32 vcc_lo, s14, 0x3f
	s_mul_i32 vcc_lo, vcc_lo, 0x22000
	s_lshl_b32 s9, s9, 7
	s_add_i32 vcc_lo, vcc_lo, s9
	v_add_u32_e32 v16, vcc_lo, v9
	s_waitcnt lgkmcnt(0)
	v_cvt_pk_bf16_f32 v28, v20, v21
	v_cvt_pk_bf16_f32 v29, v22, v23
	v_cvt_pk_bf16_f32 v30, v24, v25
	v_cvt_pk_bf16_f32 v31, v26, v27
	global_store_dwordx4 v16, v[28:31], s[12:13]
	s_waitcnt vmcnt(9)
	s_barrier
	s_add_i32 s14, s10, 0x300
	s_lshr_b32 s9, s14, 6
	s_and_b32 vcc_lo, s14, 0x3f
	s_mul_i32 s14, s9, 0x100000
	s_lshl_b32 vcc_lo, vcc_lo, 8
	s_add_i32 s14, s14, vcc_lo
	v_lshl_add_u64 v[12:13], v[10:11], 0, s[14:15]
	s_add_i32 m0, s11, 0x0
	s_nop 0
	global_load_lds_dword v[12:13], off
	v_lshl_add_u64 v[12:13], v[12:13], 0, s[16:17]
	s_add_i32 m0, s11, 0x820
	s_nop 0
	global_load_lds_dword v[12:13], off
	v_lshl_add_u64 v[12:13], v[12:13], 0, s[16:17]
	s_add_i32 m0, s11, 0x1040
	s_nop 0
	global_load_lds_dword v[12:13], off
	v_lshl_add_u64 v[12:13], v[12:13], 0, s[16:17]
	s_add_i32 m0, s11, 0x1860
	s_nop 0
	global_load_lds_dword v[12:13], off
	v_lshl_add_u64 v[12:13], v[12:13], 0, s[16:17]
	s_add_i32 m0, s11, 0x2080
	s_nop 0
	global_load_lds_dword v[12:13], off
	v_lshl_add_u64 v[12:13], v[12:13], 0, s[16:17]
	s_add_i32 m0, s11, 0x28a0
	s_nop 0
	global_load_lds_dword v[12:13], off
	v_lshl_add_u64 v[12:13], v[12:13], 0, s[16:17]
	s_add_i32 m0, s11, 0x30c0
	s_nop 0
	global_load_lds_dword v[12:13], off
	v_lshl_add_u64 v[12:13], v[12:13], 0, s[16:17]
	s_add_i32 m0, s11, 0x38e0
	s_nop 0
	global_load_lds_dword v[12:13], off
	v_add_u32_e32 v14, 0x4100, v8
	v_add_u32_e32 v15, 0x410, v14
	ds_read2_b32 v[20:21], v14 offset1:65
	ds_read2_b32 v[22:23], v14 offset0:130 offset1:195
	ds_read2_b32 v[24:25], v15 offset1:65
	ds_read2_b32 v[26:27], v15 offset0:130 offset1:195
	s_add_i32 s14, s10, 0x100
	s_lshr_b32 s9, s14, 6
	s_and_b32 vcc_lo, s14, 0x3f
	s_mul_i32 vcc_lo, vcc_lo, 0x22000
	s_lshl_b32 s9, s9, 7
	s_add_i32 vcc_lo, vcc_lo, s9
	v_add_u32_e32 v16, vcc_lo, v9
	s_waitcnt lgkmcnt(0)
	v_cvt_pk_bf16_f32 v28, v20, v21
	v_cvt_pk_bf16_f32 v29, v22, v23
	v_cvt_pk_bf16_f32 v30, v24, v25
	v_cvt_pk_bf16_f32 v31, v26, v27
	global_store_dwordx4 v16, v[28:31], s[12:13]
	s_waitcnt vmcnt(10)
	s_barrier
	v_add_u32_e32 v14, 0x8200, v8
	v_add_u32_e32 v15, 0x410, v14
	ds_read2_b32 v[20:21], v14 offset1:65
	ds_read2_b32 v[22:23], v14 offset0:130 offset1:195
	ds_read2_b32 v[24:25], v15 offset1:65
	ds_read2_b32 v[26:27], v15 offset0:130 offset1:195
	s_add_i32 s14, s10, 0x200
	s_lshr_b32 s9, s14, 6
	s_and_b32 vcc_lo, s14, 0x3f
	s_mul_i32 vcc_lo, vcc_lo, 0x22000
	s_lshl_b32 s9, s9, 7
	s_add_i32 vcc_lo, vcc_lo, s9
	v_add_u32_e32 v16, vcc_lo, v9
	s_waitcnt lgkmcnt(0)
	v_cvt_pk_bf16_f32 v28, v20, v21
	v_cvt_pk_bf16_f32 v29, v22, v23
	v_cvt_pk_bf16_f32 v30, v24, v25
	v_cvt_pk_bf16_f32 v31, v26, v27
	global_store_dwordx4 v16, v[28:31], s[12:13]
	s_waitcnt vmcnt(2)
	s_barrier
	v_mov_b32_e32 v14, v8
	v_add_u32_e32 v15, 0x410, v14
	ds_read2_b32 v[20:21], v14 offset1:65
	ds_read2_b32 v[22:23], v14 offset0:130 offset1:195
	ds_read2_b32 v[24:25], v15 offset1:65
	ds_read2_b32 v[26:27], v15 offset0:130 offset1:195
	s_add_i32 s14, s10, 0x300
	s_lshr_b32 s9, s14, 6
	s_and_b32 vcc_lo, s14, 0x3f
	s_mul_i32 vcc_lo, vcc_lo, 0x22000
	s_lshl_b32 s9, s9, 7
	s_add_i32 vcc_lo, vcc_lo, s9
	v_add_u32_e32 v16, vcc_lo, v9
	s_waitcnt lgkmcnt(0)
	v_cvt_pk_bf16_f32 v28, v20, v21
	v_cvt_pk_bf16_f32 v29, v22, v23
	v_cvt_pk_bf16_f32 v30, v24, v25
	v_cvt_pk_bf16_f32 v31, v26, v27
	global_store_dwordx4 v16, v[28:31], s[12:13]
	s_barrier
	s_branch .LBB0_92
.Lcv0_orig:
	s_ashr_i32 s6, s10, 31
	s_lshr_b32 s6, s6, 26
	s_add_i32 s6, s10, s6
	s_and_b32 s8, s6, 0xffffffc0
	s_load_dwordx16 s[40:55], s[0:1], 0x40
	s_sub_i32 s6, s10, s8
	s_lshl_b32 s6, s6, 6
	s_ashr_i32 s7, s6, 31
	v_lshlrev_b32_e32 v1, 2, v14
	s_lshl_b64 s[6:7], s[6:7], 2
	v_and_b32_e32 v2, 0xfc, v1
	v_ashrrev_i32_e32 v1, 6, v14
	s_waitcnt lgkmcnt(0)
	s_add_u32 s6, s48, s6
	v_add_u32_e32 v6, s8, v1
	s_addc_u32 s7, s49, s7
	v_mov_b32_e32 v3, 0
	v_ashrrev_i32_e32 v7, 31, v6
	v_lshl_add_u64 v[4:5], s[6:7], 0, v[2:3]
	v_lshlrev_b64 v[6:7], 14, v[6:7]
	v_lshl_add_u64 v[16:17], v[4:5], 0, v[6:7]
	v_add_u32_e32 v6, 0x200, v14
	v_ashrrev_i32_e32 v6, 6, v6
	v_add_u32_e32 v8, s8, v6
	v_ashrrev_i32_e32 v9, 31, v8
	v_add_u32_e32 v7, 0x400, v14
	v_lshlrev_b64 v[8:9], 14, v[8:9]
	v_ashrrev_i32_e32 v7, 6, v7
	v_lshl_add_u64 v[18:19], v[4:5], 0, v[8:9]
	v_add_u32_e32 v8, s8, v7
	v_ashrrev_i32_e32 v9, 31, v8
	v_lshlrev_b64 v[8:9], 14, v[8:9]
	v_lshl_add_u64 v[20:21], v[4:5], 0, v[8:9]
	v_add_u32_e32 v8, 0x600, v14
	v_ashrrev_i32_e32 v8, 6, v8
	v_add_u32_e32 v10, s8, v8
	v_ashrrev_i32_e32 v11, 31, v10
	v_add_u32_e32 v9, 0x800, v14
	v_lshlrev_b64 v[10:11], 14, v[10:11]
	v_ashrrev_i32_e32 v9, 6, v9
	s_waitcnt vmcnt(3)
	v_lshl_add_u64 v[26:27], v[4:5], 0, v[10:11]
	v_add_u32_e32 v10, s8, v9
	v_ashrrev_i32_e32 v11, 31, v10
	v_lshlrev_b64 v[10:11], 14, v[10:11]
	s_waitcnt vmcnt(1)
	v_lshl_add_u64 v[28:29], v[4:5], 0, v[10:11]
	v_add_u32_e32 v10, 0xa00, v14
	v_ashrrev_i32_e32 v10, 6, v10
	v_add_u32_e32 v12, s8, v10
	v_ashrrev_i32_e32 v13, 31, v12
	v_add_u32_e32 v11, 0xc00, v14
	v_lshlrev_b64 v[12:13], 14, v[12:13]
	v_ashrrev_i32_e32 v11, 6, v11
	v_lshl_add_u64 v[30:31], v[4:5], 0, v[12:13]
	v_add_u32_e32 v12, s8, v11
	v_ashrrev_i32_e32 v13, 31, v12
	v_lshlrev_b64 v[12:13], 14, v[12:13]
	v_lshl_add_u64 v[32:33], v[4:5], 0, v[12:13]
	v_add_u32_e32 v12, 0xe00, v14
	v_ashrrev_i32_e32 v12, 6, v12
	v_add_u32_e32 v22, s8, v12
	v_ashrrev_i32_e32 v23, 31, v22
	v_lshlrev_b64 v[22:23], 14, v[22:23]
	v_lshl_add_u64 v[4:5], v[4:5], 0, v[22:23]
	global_load_dword v23, v[16:17], off
	global_load_dword v24, v[18:19], off
	global_load_dword v25, v[20:21], off
	s_nop 0
	global_load_dword v26, v[26:27], off
	s_nop 0
	global_load_dword v27, v[28:29], off
	s_nop 0
	global_load_dword v28, v[30:31], off
	global_load_dword v29, v[32:33], off
	s_nop 0
	global_load_dword v30, v[4:5], off
	v_add_u32_e32 v21, 0, v2
	v_lshl_add_u64 v[4:5], s[48:49], 0, v[2:3]
	v_lshlrev_b32_e32 v2, 3, v14
	v_ashrrev_i32_e32 v13, 3, v14
	v_and_b32_e32 v2, 56, v2
	s_movk_i32 s6, 0x104
	v_lshl_add_u32 v22, v13, 2, 0
	v_mul_u32_u24_e32 v31, 0x104, v2
	v_mul_lo_u32 v14, v1, s6
	v_mul_lo_u32 v15, v6, s6
	v_mul_lo_u32 v16, v7, s6
	v_mul_lo_u32 v17, v8, s6
	v_mul_lo_u32 v18, v9, s6
	v_mul_lo_u32 v19, v10, s6
	v_mul_lo_u32 v20, v11, s6
	v_mul_lo_u32 v32, v12, s6
	s_lshl_b32 s13, s10, 6
	s_lshl_b32 s11, s86, 6
	v_add_u32_e32 v14, v21, v14
	v_add_u32_e32 v15, v21, v15
	v_add_u32_e32 v16, v21, v16
	v_add_u32_e32 v17, v21, v17
	v_add_u32_e32 v18, v21, v18
	v_add_u32_e32 v19, v21, v19
	v_add_u32_e32 v20, v21, v20
	v_add_u32_e32 v21, v21, v32
	v_add_u32_e32 v22, v22, v31
	s_movk_i32 s12, 0x880
	v_lshlrev_b32_e32 v2, 1, v2
	s_branch .LBB0_88

.LBB0_92:
	s_mul_hi_u32 s6, s35, 0x1480
	s_add_u32 s92, s84, 0x1208000
	s_mul_i32 s6, s6, s3
	s_addc_u32 s93, s85, 0
	s_sub_i32 s6, 0x1480, s6
	s_sub_i32 s7, s6, s3
	s_cmp_ge_u32 s6, s3
	s_cselect_b32 s6, s7, s6
	s_sub_i32 s7, s6, s3
	s_cmp_ge_u32 s6, s3
	s_cselect_b32 s6, s7, s6
	s_sub_i32 s6, s34, s6
	s_ashr_i32 s7, s6, 31
	s_abs_i32 s6, s6
	s_mul_hi_u32 s8, s6, s35
	s_mul_i32 s8, s8, s3
	s_sub_i32 s6, s6, s8
	s_sub_i32 s8, s6, s3
	s_cmp_ge_u32 s6, s3
	s_cselect_b32 s6, s8, s6
	s_sub_i32 s8, s6, s3
	s_cmp_ge_u32 s6, s3
	s_cselect_b32 s6, s8, s6
	s_xor_b32 s6, s6, s7
	s_sub_i32 s10, s6, s7
	v_mov_b32_e32 v14, v174
	s_cmpk_gt_i32 s10, 0x3ff
	s_cbranch_scc1 .LBB0_99
	s_cmpk_lg_i32 s86, 0x100
	s_cbranch_scc1 .Lcv1_orig
	s_load_dwordx2 s[6:7], s[0:1], 0x68
	v_lshrrev_b32_e32 v2, 6, v174
	v_and_b32_e32 v1, 63, v174
	v_lshrrev_b32_e32 v6, 3, v174
	v_readfirstlane_b32 s8, v2
	v_and_b32_e32 v7, 7, v174
	s_mul_i32 s9, s8, 0x1000
	v_lshlrev_b32_e32 v18, 2, v1
	v_add_u32_e32 v18, s9, v18
	s_mul_i32 s11, s8, 260
	v_mul_u32_u24_e32 v8, 0x820, v7
	v_lshl_add_u32 v8, v6, 2, v8
	v_mov_b32_e32 v9, 0x2080
	v_mul_u32_u24_e32 v9, v9, v6
	v_lshl_add_u32 v9, v7, 4, v9
	s_add_u32 s12, s84, 0x1208000
	s_addc_u32 s13, s85, 0
	s_mov_b32 s15, 0
	s_waitcnt lgkmcnt(0)
	v_mov_b32_e32 v19, 0
	v_lshl_add_u64 v[10:11], s[6:7], 0, v[18:19]
	s_mov_b32 s16, 0x8000
	s_mov_b32 s17, 0
	s_add_i32 s14, s10, 0x0
	s_lshr_b32 s9, s14, 4
	s_and_b32 vcc_lo, s14, 0xf
	s_mul_i32 s14, s9, 0x40000
	s_lshl_b32 vcc_lo, vcc_lo, 8
	s_add_i32 s14, s14, vcc_lo
	v_lshl_add_u64 v[12:13], v[10:11], 0, s[14:15]
	s_add_i32 m0, s11, 0x0
	s_nop 0
	global_load_lds_dword v[12:13], off
	v_lshl_add_u64 v[12:13], v[12:13], 0, s[16:17]
	s_add_i32 m0, s11, 0x820
	s_nop 0
	global_load_lds_dword v[12:13], off
	v_lshl_add_u64 v[12:13], v[12:13], 0, s[16:17]
	s_add_i32 m0, s11, 0x1040
	s_nop 0
	global_load_lds_dword v[12:13], off
	v_lshl_add_u64 v[12:13], v[12:13], 0, s[16:17]
	s_add_i32 m0, s11, 0x1860
	s_nop 0
	global_load_lds_dword v[12:13], off
	v_lshl_add_u64 v[12:13], v[12:13], 0, s[16:17]
	s_add_i32 m0, s11, 0x2080
	s_nop 0
	global_load_lds_dword v[12:13], off
	v_lshl_add_u64 v[12:13], v[12:13], 0, s[16:17]
	s_add_i32 m0, s11, 0x28a0
	s_nop 0
	global_load_lds_dword v[12:13], off
	v_lshl_add_u64 v[12:13], v[12:13], 0, s[16:17]
	s_add_i32 m0, s11, 0x30c0
	s_nop 0
	global_load_lds_dword v[12:13], off
	v_lshl_add_u64 v[12:13], v[12:13], 0, s[16:17]
	s_add_i32 m0, s11, 0x38e0
	s_nop 0
	global_load_lds_dword v[12:13], off
	s_add_i32 s14, s10, 0x100
	s_lshr_b32 s9, s14, 4
	s_and_b32 vcc_lo, s14, 0xf
	s_mul_i32 s14, s9, 0x40000
	s_lshl_b32 vcc_lo, vcc_lo, 8
	s_add_i32 s14, s14, vcc_lo
	v_lshl_add_u64 v[12:13], v[10:11], 0, s[14:15]
	s_add_i32 m0, s11, 0x4100
	s_nop 0
	global_load_lds_dword v[12:13], off
	v_lshl_add_u64 v[12:13], v[12:13], 0, s[16:17]
	s_add_i32 m0, s11, 0x4920
	s_nop 0
	global_load_lds_dword v[12:13], off
	v_lshl_add_u64 v[12:13], v[12:13], 0, s[16:17]
	s_add_i32 m0, s11, 0x5140
	s_nop 0
	global_load_lds_dword v[12:13], off
	v_lshl_add_u64 v[12:13], v[12:13], 0, s[16:17]
	s_add_i32 m0, s11, 0x5960
	s_nop 0
	global_load_lds_dword v[12:13], off
	v_lshl_add_u64 v[12:13], v[12:13], 0, s[16:17]
	s_add_i32 m0, s11, 0x6180
	s_nop 0
	global_load_lds_dword v[12:13], off
	v_lshl_add_u64 v[12:13], v[12:13], 0, s[16:17]
	s_add_i32 m0, s11, 0x69a0
	s_nop 0
	global_load_lds_dword v[12:13], off
	v_lshl_add_u64 v[12:13], v[12:13], 0, s[16:17]
	s_add_i32 m0, s11, 0x71c0
	s_nop 0
	global_load_lds_dword v[12:13], off
	v_lshl_add_u64 v[12:13], v[12:13], 0, s[16:17]
	s_add_i32 m0, s11, 0x79e0
	s_nop 0
	global_load_lds_dword v[12:13], off
	s_waitcnt vmcnt(8)
	s_barrier
	s_add_i32 s14, s10, 0x200
	s_lshr_b32 s9, s14, 4
	s_and_b32 vcc_lo, s14, 0xf
	s_mul_i32 s14, s9, 0x40000
	s_lshl_b32 vcc_lo, vcc_lo, 8
	s_add_i32 s14, s14, vcc_lo
	v_lshl_add_u64 v[12:13], v[10:11], 0, s[14:15]
	s_add_i32 m0, s11, 0x8200
	s_nop 0
	global_load_lds_dword v[12:13], off
	v_lshl_add_u64 v[12:13], v[12:13], 0, s[16:17]
	s_add_i32 m0, s11, 0x8a20
	s_nop 0
	global_load_lds_dword v[12:13], off
	v_lshl_add_u64 v[12:13], v[12:13], 0, s[16:17]
	s_add_i32 m0, s11, 0x9240
	s_nop 0
	global_load_lds_dword v[12:13], off
	v_lshl_add_u64 v[12:13], v[12:13], 0, s[16:17]
	s_add_i32 m0, s11, 0x9a60
	s_nop 0
	global_load_lds_dword v[12:13], off
	v_lshl_add_u64 v[12:13], v[12:13], 0, s[16:17]
	s_add_i32 m0, s11, 0xa280
	s_nop 0
	global_load_lds_dword v[12:13], off
	v_lshl_add_u64 v[12:13], v[12:13], 0, s[16:17]
	s_add_i32 m0, s11, 0xaaa0
	s_nop 0
	global_load_lds_dword v[12:13], off
	v_lshl_add_u64 v[12:13], v[12:13], 0, s[16:17]
	s_add_i32 m0, s11, 0xb2c0
	s_nop 0
	global_load_lds_dword v[12:13], off
	v_lshl_add_u64 v[12:13], v[12:13], 0, s[16:17]
	s_add_i32 m0, s11, 0xbae0
	s_nop 0
	global_load_lds_dword v[12:13], off
	v_mov_b32_e32 v14, v8
	v_add_u32_e32 v15, 0x410, v14
	ds_read2_b32 v[20:21], v14 offset1:65
	ds_read2_b32 v[22:23], v14 offset0:130 offset1:195
	ds_read2_b32 v[24:25], v15 offset1:65
	ds_read2_b32 v[26:27], v15 offset0:130 offset1:195
	s_add_i32 s14, s10, 0x0
	s_lshr_b32 s9, s14, 4
	s_and_b32 vcc_lo, s14, 0xf
	s_mul_i32 vcc_lo, vcc_lo, 0x82000
	s_lshl_b32 s9, s9, 7
	s_add_i32 vcc_lo, vcc_lo, s9
	v_add_u32_e32 v16, vcc_lo, v9
	s_waitcnt lgkmcnt(0)
	v_cvt_pk_bf16_f32 v28, v20, v21
	v_cvt_pk_bf16_f32 v29, v22, v23
	v_cvt_pk_bf16_f32 v30, v24, v25
	v_cvt_pk_bf16_f32 v31, v26, v27
	global_store_dwordx4 v16, v[28:31], s[12:13]
	s_waitcnt vmcnt(9)
	s_barrier
	s_add_i32 s14, s10, 0x300
	s_lshr_b32 s9, s14, 4
	s_and_b32 vcc_lo, s14, 0xf
	s_mul_i32 s14, s9, 0x40000
	s_lshl_b32 vcc_lo, vcc_lo, 8
	s_add_i32 s14, s14, vcc_lo
	v_lshl_add_u64 v[12:13], v[10:11], 0, s[14:15]
	s_add_i32 m0, s11, 0x0
	s_nop 0
	global_load_lds_dword v[12:13], off
	v_lshl_add_u64 v[12:13], v[12:13], 0, s[16:17]
	s_add_i32 m0, s11, 0x820
	s_nop 0
	global_load_lds_dword v[12:13], off
	v_lshl_add_u64 v[12:13], v[12:13], 0, s[16:17]
	s_add_i32 m0, s11, 0x1040
	s_nop 0
	global_load_lds_dword v[12:13], off
	v_lshl_add_u64 v[12:13], v[12:13], 0, s[16:17]
	s_add_i32 m0, s11, 0x1860
	s_nop 0
	global_load_lds_dword v[12:13], off
	v_lshl_add_u64 v[12:13], v[12:13], 0, s[16:17]
	s_add_i32 m0, s11, 0x2080
	s_nop 0
	global_load_lds_dword v[12:13], off
	v_lshl_add_u64 v[12:13], v[12:13], 0, s[16:17]
	s_add_i32 m0, s11, 0x28a0
	s_nop 0
	global_load_lds_dword v[12:13], off
	v_lshl_add_u64 v[12:13], v[12:13], 0, s[16:17]
	s_add_i32 m0, s11, 0x30c0
	s_nop 0
	global_load_lds_dword v[12:13], off
	v_lshl_add_u64 v[12:13], v[12:13], 0, s[16:17]
	s_add_i32 m0, s11, 0x38e0
	s_nop 0
	global_load_lds_dword v[12:13], off
	v_add_u32_e32 v14, 0x4100, v8
	v_add_u32_e32 v15, 0x410, v14
	ds_read2_b32 v[20:21], v14 offset1:65
	ds_read2_b32 v[22:23], v14 offset0:130 offset1:195
	ds_read2_b32 v[24:25], v15 offset1:65
	ds_read2_b32 v[26:27], v15 offset0:130 offset1:195
	s_add_i32 s14, s10, 0x100
	s_lshr_b32 s9, s14, 4
	s_and_b32 vcc_lo, s14, 0xf
	s_mul_i32 vcc_lo, vcc_lo, 0x82000
	s_lshl_b32 s9, s9, 7
	s_add_i32 vcc_lo, vcc_lo, s9
	v_add_u32_e32 v16, vcc_lo, v9
	s_waitcnt lgkmcnt(0)
	v_cvt_pk_bf16_f32 v28, v20, v21
	v_cvt_pk_bf16_f32 v29, v22, v23
	v_cvt_pk_bf16_f32 v30, v24, v25
	v_cvt_pk_bf16_f32 v31, v26, v27
	global_store_dwordx4 v16, v[28:31], s[12:13]
	s_waitcnt vmcnt(10)
	s_barrier
	v_add_u32_e32 v14, 0x8200, v8
	v_add_u32_e32 v15, 0x410, v14
	ds_read2_b32 v[20:21], v14 offset1:65
	ds_read2_b32 v[22:23], v14 offset0:130 offset1:195
	ds_read2_b32 v[24:25], v15 offset1:65
	ds_read2_b32 v[26:27], v15 offset0:130 offset1:195
	s_add_i32 s14, s10, 0x200
	s_lshr_b32 s9, s14, 4
	s_and_b32 vcc_lo, s14, 0xf
	s_mul_i32 vcc_lo, vcc_lo, 0x82000
	s_lshl_b32 s9, s9, 7
	s_add_i32 vcc_lo, vcc_lo, s9
	v_add_u32_e32 v16, vcc_lo, v9
	s_waitcnt lgkmcnt(0)
	v_cvt_pk_bf16_f32 v28, v20, v21
	v_cvt_pk_bf16_f32 v29, v22, v23
	v_cvt_pk_bf16_f32 v30, v24, v25
	v_cvt_pk_bf16_f32 v31, v26, v27
	global_store_dwordx4 v16, v[28:31], s[12:13]
	s_waitcnt vmcnt(2)
	s_barrier
	v_mov_b32_e32 v14, v8
	v_add_u32_e32 v15, 0x410, v14
	ds_read2_b32 v[20:21], v14 offset1:65
	ds_read2_b32 v[22:23], v14 offset0:130 offset1:195
	ds_read2_b32 v[24:25], v15 offset1:65
	ds_read2_b32 v[26:27], v15 offset0:130 offset1:195
	s_add_i32 s14, s10, 0x300
	s_lshr_b32 s9, s14, 4
	s_and_b32 vcc_lo, s14, 0xf
	s_mul_i32 vcc_lo, vcc_lo, 0x82000
	s_lshl_b32 s9, s9, 7
	s_add_i32 vcc_lo, vcc_lo, s9
	v_add_u32_e32 v16, vcc_lo, v9
	s_waitcnt lgkmcnt(0)
	v_cvt_pk_bf16_f32 v28, v20, v21
	v_cvt_pk_bf16_f32 v29, v22, v23
	v_cvt_pk_bf16_f32 v30, v24, v25
	v_cvt_pk_bf16_f32 v31, v26, v27
	global_store_dwordx4 v16, v[28:31], s[12:13]
	s_barrier
	s_branch .LBB0_99
.Lcv1_orig:
	s_ashr_i32 s6, s10, 31
	s_lshr_b32 s6, s6, 28
	s_add_i32 s6, s10, s6
	s_lshl_b32 s7, s6, 2
	s_and_b32 s6, s6, 0x3fffff0
	s_load_dwordx16 s[40:55], s[0:1], 0x40
	s_sub_i32 s6, s10, s6
	s_lshl_b32 s6, s6, 6
	s_and_b32 s8, s7, 0xffffffc0
	s_ashr_i32 s7, s6, 31
	v_lshlrev_b32_e32 v1, 2, v14
	s_lshl_b64 s[6:7], s[6:7], 2
	v_and_b32_e32 v2, 0xfc, v1
	v_ashrrev_i32_e32 v1, 6, v14
	s_waitcnt lgkmcnt(0)
	s_add_u32 s6, s50, s6
	v_add_u32_e32 v6, s8, v1
	s_addc_u32 s7, s51, s7
	v_mov_b32_e32 v3, 0
	v_ashrrev_i32_e32 v7, 31, v6
	v_lshl_add_u64 v[4:5], s[6:7], 0, v[2:3]
	v_lshlrev_b64 v[6:7], 12, v[6:7]
	v_lshl_add_u64 v[16:17], v[4:5], 0, v[6:7]
	v_add_u32_e32 v6, 0x200, v14
	v_ashrrev_i32_e32 v6, 6, v6
	v_add_u32_e32 v8, s8, v6
	v_ashrrev_i32_e32 v9, 31, v8
	v_add_u32_e32 v7, 0x400, v14
	v_lshlrev_b64 v[8:9], 12, v[8:9]
	v_ashrrev_i32_e32 v7, 6, v7
	v_lshl_add_u64 v[18:19], v[4:5], 0, v[8:9]
	v_add_u32_e32 v8, s8, v7
	v_ashrrev_i32_e32 v9, 31, v8
	v_lshlrev_b64 v[8:9], 12, v[8:9]
	v_lshl_add_u64 v[20:21], v[4:5], 0, v[8:9]
	v_add_u32_e32 v8, 0x600, v14
	v_ashrrev_i32_e32 v8, 6, v8
	v_add_u32_e32 v10, s8, v8
	v_ashrrev_i32_e32 v11, 31, v10
	v_add_u32_e32 v9, 0x800, v14
	v_lshlrev_b64 v[10:11], 12, v[10:11]
	v_ashrrev_i32_e32 v9, 6, v9
	s_waitcnt vmcnt(3)
	v_lshl_add_u64 v[26:27], v[4:5], 0, v[10:11]
	v_add_u32_e32 v10, s8, v9
	v_ashrrev_i32_e32 v11, 31, v10
	v_lshlrev_b64 v[10:11], 12, v[10:11]
	s_waitcnt vmcnt(1)
	v_lshl_add_u64 v[28:29], v[4:5], 0, v[10:11]
	v_add_u32_e32 v10, 0xa00, v14
	v_ashrrev_i32_e32 v10, 6, v10
	v_add_u32_e32 v12, s8, v10
	v_ashrrev_i32_e32 v13, 31, v12
	v_add_u32_e32 v11, 0xc00, v14
	v_lshlrev_b64 v[12:13], 12, v[12:13]
	v_ashrrev_i32_e32 v11, 6, v11
	v_lshl_add_u64 v[30:31], v[4:5], 0, v[12:13]
	v_add_u32_e32 v12, s8, v11
	v_ashrrev_i32_e32 v13, 31, v12
	v_lshlrev_b64 v[12:13], 12, v[12:13]
	v_lshl_add_u64 v[32:33], v[4:5], 0, v[12:13]
	v_add_u32_e32 v12, 0xe00, v14
	v_ashrrev_i32_e32 v12, 6, v12
	v_add_u32_e32 v22, s8, v12
	v_ashrrev_i32_e32 v23, 31, v22
	v_lshlrev_b64 v[22:23], 12, v[22:23]
	v_lshl_add_u64 v[4:5], v[4:5], 0, v[22:23]
	global_load_dword v23, v[16:17], off
	global_load_dword v24, v[18:19], off
	global_load_dword v25, v[20:21], off
	s_nop 0
	global_load_dword v26, v[26:27], off
	s_nop 0
	global_load_dword v27, v[28:29], off
	s_nop 0
	global_load_dword v28, v[30:31], off
	global_load_dword v29, v[32:33], off
	s_nop 0
	global_load_dword v30, v[4:5], off
	v_add_u32_e32 v21, 0, v2
	v_lshl_add_u64 v[4:5], s[50:51], 0, v[2:3]
	v_lshlrev_b32_e32 v2, 3, v14
	v_ashrrev_i32_e32 v13, 3, v14
	v_and_b32_e32 v2, 56, v2
	s_movk_i32 s6, 0x104
	v_lshl_add_u32 v22, v13, 2, 0
	v_mul_u32_u24_e32 v31, 0x104, v2
	v_mul_lo_u32 v14, v1, s6
	v_mul_lo_u32 v15, v6, s6
	v_mul_lo_u32 v16, v7, s6
	v_mul_lo_u32 v17, v8, s6
	v_mul_lo_u32 v18, v9, s6
	v_mul_lo_u32 v19, v10, s6
	v_mul_lo_u32 v20, v11, s6
	v_mul_lo_u32 v32, v12, s6
	s_lshl_b32 s13, s10, 6
	s_lshl_b32 s11, s86, 6
	v_add_u32_e32 v14, v21, v14
	v_add_u32_e32 v15, v21, v15
	v_add_u32_e32 v16, v21, v16
	v_add_u32_e32 v17, v21, v17
	v_add_u32_e32 v18, v21, v18
	v_add_u32_e32 v19, v21, v19
	v_add_u32_e32 v20, v21, v20
	v_add_u32_e32 v21, v21, v32
	v_add_u32_e32 v22, v22, v31
	s_movk_i32 s12, 0x2080
	v_lshlrev_b32_e32 v2, 1, v2
	s_branch .LBB0_95

.LBB0_113:
	s_mul_hi_u32 s6, s35, 0x1b00
	s_add_u32 s18, s84, 0x1f78000
	s_mul_i32 s6, s6, s3
	s_addc_u32 s19, s85, 0
	s_sub_i32 s6, 0x1b00, s6
	s_sub_i32 s7, s6, s3
	s_cmp_ge_u32 s6, s3
	s_cselect_b32 s6, s7, s6
	s_sub_i32 s7, s6, s3
	s_cmp_ge_u32 s6, s3
	s_cselect_b32 s6, s7, s6
	s_sub_i32 s6, s34, s6
	s_ashr_i32 s7, s6, 31
	s_abs_i32 s6, s6
	s_mul_hi_u32 s8, s6, s35
	s_mul_i32 s8, s8, s3
	s_sub_i32 s6, s6, s8
	s_sub_i32 s8, s6, s3
	s_cmp_ge_u32 s6, s3
	s_cselect_b32 s6, s8, s6
	s_sub_i32 s8, s6, s3
	s_cmp_ge_u32 s6, s3
	s_cselect_b32 s6, s8, s6
	s_xor_b32 s6, s6, s7
	s_sub_i32 s10, s6, s7
	v_writelane_b32 v192, s28, 33
	v_mov_b32_e32 v14, v174
	s_cmpk_gt_i32 s10, 0x3ff
	v_writelane_b32 v192, s29, 34
	s_cbranch_scc1 .LBB0_120
	s_cmpk_lg_i32 s86, 0x100
	s_cbranch_scc1 .Lcv2_orig
	s_load_dwordx2 s[6:7], s[0:1], 0x60
	v_lshrrev_b32_e32 v2, 6, v174
	v_and_b32_e32 v1, 63, v174
	v_lshrrev_b32_e32 v6, 3, v174
	v_readfirstlane_b32 s8, v2
	v_and_b32_e32 v7, 7, v174
	s_mul_i32 s9, s8, 0x4000
	v_lshlrev_b32_e32 v18, 2, v1
	v_add_u32_e32 v18, s9, v18
	s_mul_i32 s11, s8, 260
	v_mul_u32_u24_e32 v8, 0x820, v7
	v_lshl_add_u32 v8, v6, 2, v8
	v_mov_b32_e32 v9, 0x880
	v_mul_u32_u24_e32 v9, v9, v6
	v_lshl_add_u32 v9, v7, 4, v9
	s_add_u32 s12, s84, 0x1f78000
	s_addc_u32 s13, s85, 0
	s_mov_b32 s15, 0
	s_waitcnt lgkmcnt(0)
	s_add_u32 s6, s6, 0x1000000
	s_addc_u32 s7, s7, 0
	v_mov_b32_e32 v19, 0
	v_lshl_add_u64 v[10:11], s[6:7], 0, v[18:19]
	s_mov_b32 s16, 0x20000
	s_mov_b32 s17, 0
	s_add_i32 s14, s10, 0x0
	s_lshr_b32 s9, s14, 6
	s_and_b32 vcc_lo, s14, 0x3f
	s_mul_i32 s14, s9, 0x100000
	s_lshl_b32 vcc_lo, vcc_lo, 8
	s_add_i32 s14, s14, vcc_lo
	v_lshl_add_u64 v[12:13], v[10:11], 0, s[14:15]
	s_add_i32 m0, s11, 0x0
	s_nop 0
	global_load_lds_dword v[12:13], off
	v_lshl_add_u64 v[12:13], v[12:13], 0, s[16:17]
	s_add_i32 m0, s11, 0x820
	s_nop 0
	global_load_lds_dword v[12:13], off
	v_lshl_add_u64 v[12:13], v[12:13], 0, s[16:17]
	s_add_i32 m0, s11, 0x1040
	s_nop 0
	global_load_lds_dword v[12:13], off
	v_lshl_add_u64 v[12:13], v[12:13], 0, s[16:17]
	s_add_i32 m0, s11, 0x1860
	s_nop 0
	global_load_lds_dword v[12:13], off
	v_lshl_add_u64 v[12:13], v[12:13], 0, s[16:17]
	s_add_i32 m0, s11, 0x2080
	s_nop 0
	global_load_lds_dword v[12:13], off
	v_lshl_add_u64 v[12:13], v[12:13], 0, s[16:17]
	s_add_i32 m0, s11, 0x28a0
	s_nop 0
	global_load_lds_dword v[12:13], off
	v_lshl_add_u64 v[12:13], v[12:13], 0, s[16:17]
	s_add_i32 m0, s11, 0x30c0
	s_nop 0
	global_load_lds_dword v[12:13], off
	v_lshl_add_u64 v[12:13], v[12:13], 0, s[16:17]
	s_add_i32 m0, s11, 0x38e0
	s_nop 0
	global_load_lds_dword v[12:13], off
	s_add_i32 s14, s10, 0x100
	s_lshr_b32 s9, s14, 6
	s_and_b32 vcc_lo, s14, 0x3f
	s_mul_i32 s14, s9, 0x100000
	s_lshl_b32 vcc_lo, vcc_lo, 8
	s_add_i32 s14, s14, vcc_lo
	v_lshl_add_u64 v[12:13], v[10:11], 0, s[14:15]
	s_add_i32 m0, s11, 0x4100
	s_nop 0
	global_load_lds_dword v[12:13], off
	v_lshl_add_u64 v[12:13], v[12:13], 0, s[16:17]
	s_add_i32 m0, s11, 0x4920
	s_nop 0
	global_load_lds_dword v[12:13], off
	v_lshl_add_u64 v[12:13], v[12:13], 0, s[16:17]
	s_add_i32 m0, s11, 0x5140
	s_nop 0
	global_load_lds_dword v[12:13], off
	v_lshl_add_u64 v[12:13], v[12:13], 0, s[16:17]
	s_add_i32 m0, s11, 0x5960
	s_nop 0
	global_load_lds_dword v[12:13], off
	v_lshl_add_u64 v[12:13], v[12:13], 0, s[16:17]
	s_add_i32 m0, s11, 0x6180
	s_nop 0
	global_load_lds_dword v[12:13], off
	v_lshl_add_u64 v[12:13], v[12:13], 0, s[16:17]
	s_add_i32 m0, s11, 0x69a0
	s_nop 0
	global_load_lds_dword v[12:13], off
	v_lshl_add_u64 v[12:13], v[12:13], 0, s[16:17]
	s_add_i32 m0, s11, 0x71c0
	s_nop 0
	global_load_lds_dword v[12:13], off
	v_lshl_add_u64 v[12:13], v[12:13], 0, s[16:17]
	s_add_i32 m0, s11, 0x79e0
	s_nop 0
	global_load_lds_dword v[12:13], off
	s_waitcnt vmcnt(8)
	s_barrier
	s_add_i32 s14, s10, 0x200
	s_lshr_b32 s9, s14, 6
	s_and_b32 vcc_lo, s14, 0x3f
	s_mul_i32 s14, s9, 0x100000
	s_lshl_b32 vcc_lo, vcc_lo, 8
	s_add_i32 s14, s14, vcc_lo
	v_lshl_add_u64 v[12:13], v[10:11], 0, s[14:15]
	s_add_i32 m0, s11, 0x8200
	s_nop 0
	global_load_lds_dword v[12:13], off
	v_lshl_add_u64 v[12:13], v[12:13], 0, s[16:17]
	s_add_i32 m0, s11, 0x8a20
	s_nop 0
	global_load_lds_dword v[12:13], off
	v_lshl_add_u64 v[12:13], v[12:13], 0, s[16:17]
	s_add_i32 m0, s11, 0x9240
	s_nop 0
	global_load_lds_dword v[12:13], off
	v_lshl_add_u64 v[12:13], v[12:13], 0, s[16:17]
	s_add_i32 m0, s11, 0x9a60
	s_nop 0
	global_load_lds_dword v[12:13], off
	v_lshl_add_u64 v[12:13], v[12:13], 0, s[16:17]
	s_add_i32 m0, s11, 0xa280
	s_nop 0
	global_load_lds_dword v[12:13], off
	v_lshl_add_u64 v[12:13], v[12:13], 0, s[16:17]
	s_add_i32 m0, s11, 0xaaa0
	s_nop 0
	global_load_lds_dword v[12:13], off
	v_lshl_add_u64 v[12:13], v[12:13], 0, s[16:17]
	s_add_i32 m0, s11, 0xb2c0
	s_nop 0
	global_load_lds_dword v[12:13], off
	v_lshl_add_u64 v[12:13], v[12:13], 0, s[16:17]
	s_add_i32 m0, s11, 0xbae0
	s_nop 0
	global_load_lds_dword v[12:13], off
	v_mov_b32_e32 v14, v8
	v_add_u32_e32 v15, 0x410, v14
	ds_read2_b32 v[20:21], v14 offset1:65
	ds_read2_b32 v[22:23], v14 offset0:130 offset1:195
	ds_read2_b32 v[24:25], v15 offset1:65
	ds_read2_b32 v[26:27], v15 offset0:130 offset1:195
	s_add_i32 s14, s10, 0x0
	s_lshr_b32 s9, s14, 6
	s_and_b32 vcc_lo, s14, 0x3f
	s_mul_i32 vcc_lo, vcc_lo, 0x22000
	s_lshl_b32 s9, s9, 7
	s_add_i32 vcc_lo, vcc_lo, s9
	v_add_u32_e32 v16, vcc_lo, v9
	s_waitcnt lgkmcnt(0)
	v_cvt_pk_bf16_f32 v28, v20, v21
	v_cvt_pk_bf16_f32 v29, v22, v23
	v_cvt_pk_bf16_f32 v30, v24, v25
	v_cvt_pk_bf16_f32 v31, v26, v27
	global_store_dwordx4 v16, v[28:31], s[12:13]
	s_waitcnt vmcnt(9)
	s_barrier
	s_add_i32 s14, s10, 0x300
	s_lshr_b32 s9, s14, 6
	s_and_b32 vcc_lo, s14, 0x3f
	s_mul_i32 s14, s9, 0x100000
	s_lshl_b32 vcc_lo, vcc_lo, 8
	s_add_i32 s14, s14, vcc_lo
	v_lshl_add_u64 v[12:13], v[10:11], 0, s[14:15]
	s_add_i32 m0, s11, 0x0
	s_nop 0
	global_load_lds_dword v[12:13], off
	v_lshl_add_u64 v[12:13], v[12:13], 0, s[16:17]
	s_add_i32 m0, s11, 0x820
	s_nop 0
	global_load_lds_dword v[12:13], off
	v_lshl_add_u64 v[12:13], v[12:13], 0, s[16:17]
	s_add_i32 m0, s11, 0x1040
	s_nop 0
	global_load_lds_dword v[12:13], off
	v_lshl_add_u64 v[12:13], v[12:13], 0, s[16:17]
	s_add_i32 m0, s11, 0x1860
	s_nop 0
	global_load_lds_dword v[12:13], off
	v_lshl_add_u64 v[12:13], v[12:13], 0, s[16:17]
	s_add_i32 m0, s11, 0x2080
	s_nop 0
	global_load_lds_dword v[12:13], off
	v_lshl_add_u64 v[12:13], v[12:13], 0, s[16:17]
	s_add_i32 m0, s11, 0x28a0
	s_nop 0
	global_load_lds_dword v[12:13], off
	v_lshl_add_u64 v[12:13], v[12:13], 0, s[16:17]
	s_add_i32 m0, s11, 0x30c0
	s_nop 0
	global_load_lds_dword v[12:13], off
	v_lshl_add_u64 v[12:13], v[12:13], 0, s[16:17]
	s_add_i32 m0, s11, 0x38e0
	s_nop 0
	global_load_lds_dword v[12:13], off
	v_add_u32_e32 v14, 0x4100, v8
	v_add_u32_e32 v15, 0x410, v14
	ds_read2_b32 v[20:21], v14 offset1:65
	ds_read2_b32 v[22:23], v14 offset0:130 offset1:195
	ds_read2_b32 v[24:25], v15 offset1:65
	ds_read2_b32 v[26:27], v15 offset0:130 offset1:195
	s_add_i32 s14, s10, 0x100
	s_lshr_b32 s9, s14, 6
	s_and_b32 vcc_lo, s14, 0x3f
	s_mul_i32 vcc_lo, vcc_lo, 0x22000
	s_lshl_b32 s9, s9, 7
	s_add_i32 vcc_lo, vcc_lo, s9
	v_add_u32_e32 v16, vcc_lo, v9
	s_waitcnt lgkmcnt(0)
	v_cvt_pk_bf16_f32 v28, v20, v21
	v_cvt_pk_bf16_f32 v29, v22, v23
	v_cvt_pk_bf16_f32 v30, v24, v25
	v_cvt_pk_bf16_f32 v31, v26, v27
	global_store_dwordx4 v16, v[28:31], s[12:13]
	s_waitcnt vmcnt(10)
	s_barrier
	v_add_u32_e32 v14, 0x8200, v8
	v_add_u32_e32 v15, 0x410, v14
	ds_read2_b32 v[20:21], v14 offset1:65
	ds_read2_b32 v[22:23], v14 offset0:130 offset1:195
	ds_read2_b32 v[24:25], v15 offset1:65
	ds_read2_b32 v[26:27], v15 offset0:130 offset1:195
	s_add_i32 s14, s10, 0x200
	s_lshr_b32 s9, s14, 6
	s_and_b32 vcc_lo, s14, 0x3f
	s_mul_i32 vcc_lo, vcc_lo, 0x22000
	s_lshl_b32 s9, s9, 7
	s_add_i32 vcc_lo, vcc_lo, s9
	v_add_u32_e32 v16, vcc_lo, v9
	s_waitcnt lgkmcnt(0)
	v_cvt_pk_bf16_f32 v28, v20, v21
	v_cvt_pk_bf16_f32 v29, v22, v23
	v_cvt_pk_bf16_f32 v30, v24, v25
	v_cvt_pk_bf16_f32 v31, v26, v27
	global_store_dwordx4 v16, v[28:31], s[12:13]
	s_waitcnt vmcnt(2)
	s_barrier
	v_mov_b32_e32 v14, v8
	v_add_u32_e32 v15, 0x410, v14
	ds_read2_b32 v[20:21], v14 offset1:65
	ds_read2_b32 v[22:23], v14 offset0:130 offset1:195
	ds_read2_b32 v[24:25], v15 offset1:65
	ds_read2_b32 v[26:27], v15 offset0:130 offset1:195
	s_add_i32 s14, s10, 0x300
	s_lshr_b32 s9, s14, 6
	s_and_b32 vcc_lo, s14, 0x3f
	s_mul_i32 vcc_lo, vcc_lo, 0x22000
	s_lshl_b32 s9, s9, 7
	s_add_i32 vcc_lo, vcc_lo, s9
	v_add_u32_e32 v16, vcc_lo, v9
	s_waitcnt lgkmcnt(0)
	v_cvt_pk_bf16_f32 v28, v20, v21
	v_cvt_pk_bf16_f32 v29, v22, v23
	v_cvt_pk_bf16_f32 v30, v24, v25
	v_cvt_pk_bf16_f32 v31, v26, v27
	global_store_dwordx4 v16, v[28:31], s[12:13]
	s_barrier
	s_branch .LBB0_120
.Lcv2_orig:
	s_load_dwordx16 s[40:55], s[0:1], 0x40
	v_lshlrev_b32_e32 v1, 2, v14
	v_and_b32_e32 v2, 0xfc, v1
	v_ashrrev_i32_e32 v1, 6, v14
	v_mov_b32_e32 v3, 0
	s_waitcnt lgkmcnt(0)
	s_add_u32 s6, s48, 0x1000000
	s_addc_u32 s7, s49, 0
	s_ashr_i32 s8, s10, 31
	s_lshr_b32 s8, s8, 26
	s_add_i32 s8, s10, s8
	s_and_b32 s11, s8, 0xffffffc0
	s_sub_i32 s8, s10, s11
	s_lshl_b32 s8, s8, 6
	s_ashr_i32 s9, s8, 31
	s_lshl_b64 s[8:9], s[8:9], 2
	s_add_u32 s8, s6, s8
	v_add_u32_e32 v6, s11, v1
	s_addc_u32 s9, s7, s9
	v_ashrrev_i32_e32 v7, 31, v6
	v_lshl_add_u64 v[4:5], s[8:9], 0, v[2:3]
	v_lshlrev_b64 v[6:7], 14, v[6:7]
	v_lshl_add_u64 v[16:17], v[4:5], 0, v[6:7]
	v_add_u32_e32 v6, 0x200, v14
	v_ashrrev_i32_e32 v6, 6, v6
	v_add_u32_e32 v8, s11, v6
	v_ashrrev_i32_e32 v9, 31, v8
	v_add_u32_e32 v7, 0x400, v14
	v_lshlrev_b64 v[8:9], 14, v[8:9]
	v_ashrrev_i32_e32 v7, 6, v7
	v_lshl_add_u64 v[18:19], v[4:5], 0, v[8:9]
	v_add_u32_e32 v8, s11, v7
	v_ashrrev_i32_e32 v9, 31, v8
	v_lshlrev_b64 v[8:9], 14, v[8:9]
	v_lshl_add_u64 v[20:21], v[4:5], 0, v[8:9]
	v_add_u32_e32 v8, 0x600, v14
	v_ashrrev_i32_e32 v8, 6, v8
	v_add_u32_e32 v10, s11, v8
	v_ashrrev_i32_e32 v11, 31, v10
	v_add_u32_e32 v9, 0x800, v14
	v_lshlrev_b64 v[10:11], 14, v[10:11]
	v_ashrrev_i32_e32 v9, 6, v9
	s_waitcnt vmcnt(3)
	v_lshl_add_u64 v[26:27], v[4:5], 0, v[10:11]
	v_add_u32_e32 v10, s11, v9
	v_ashrrev_i32_e32 v11, 31, v10
	v_lshlrev_b64 v[10:11], 14, v[10:11]
	s_waitcnt vmcnt(1)
	v_lshl_add_u64 v[28:29], v[4:5], 0, v[10:11]
	v_add_u32_e32 v10, 0xa00, v14
	v_ashrrev_i32_e32 v10, 6, v10
	v_add_u32_e32 v12, s11, v10
	v_ashrrev_i32_e32 v13, 31, v12
	v_add_u32_e32 v11, 0xc00, v14
	v_lshlrev_b64 v[12:13], 14, v[12:13]
	v_ashrrev_i32_e32 v11, 6, v11
	v_lshl_add_u64 v[30:31], v[4:5], 0, v[12:13]
	v_add_u32_e32 v12, s11, v11
	v_ashrrev_i32_e32 v13, 31, v12
	v_lshlrev_b64 v[12:13], 14, v[12:13]
	v_lshl_add_u64 v[32:33], v[4:5], 0, v[12:13]
	v_add_u32_e32 v12, 0xe00, v14
	v_ashrrev_i32_e32 v12, 6, v12
	v_add_u32_e32 v22, s11, v12
	v_ashrrev_i32_e32 v23, 31, v22
	v_lshlrev_b64 v[22:23], 14, v[22:23]
	v_lshl_add_u64 v[4:5], v[4:5], 0, v[22:23]
	global_load_dword v23, v[16:17], off
	global_load_dword v24, v[18:19], off
	global_load_dword v25, v[20:21], off
	s_nop 0
	global_load_dword v26, v[26:27], off
	s_nop 0
	global_load_dword v27, v[28:29], off
	s_nop 0
	global_load_dword v28, v[30:31], off
	global_load_dword v29, v[32:33], off
	s_nop 0
	global_load_dword v30, v[4:5], off
	v_add_u32_e32 v21, 0, v2
	v_lshl_add_u64 v[4:5], s[6:7], 0, v[2:3]
	v_lshlrev_b32_e32 v2, 3, v14
	v_ashrrev_i32_e32 v13, 3, v14
	v_and_b32_e32 v2, 56, v2
	s_movk_i32 s6, 0x104
	v_lshl_add_u32 v22, v13, 2, 0
	v_mul_u32_u24_e32 v31, 0x104, v2
	v_mul_lo_u32 v14, v1, s6
	v_mul_lo_u32 v15, v6, s6
	v_mul_lo_u32 v16, v7, s6
	v_mul_lo_u32 v17, v8, s6
	v_mul_lo_u32 v18, v9, s6
	v_mul_lo_u32 v19, v10, s6
	v_mul_lo_u32 v20, v11, s6
	v_mul_lo_u32 v32, v12, s6
	s_lshl_b32 s13, s10, 6
	s_lshl_b32 s11, s86, 6
	v_add_u32_e32 v14, v21, v14
	v_add_u32_e32 v15, v21, v15
	v_add_u32_e32 v16, v21, v16
	v_add_u32_e32 v17, v21, v17
	v_add_u32_e32 v18, v21, v18
	v_add_u32_e32 v19, v21, v19
	v_add_u32_e32 v20, v21, v20
	v_add_u32_e32 v21, v21, v32
	v_add_u32_e32 v22, v22, v31
	s_movk_i32 s12, 0x880
	v_lshlrev_b32_e32 v2, 1, v2
	s_branch .LBB0_116

.LBB0_120:
	s_mul_hi_u32 s6, s35, 0x1f00
	s_add_u32 s56, s84, 0x27f8000
	s_mul_i32 s6, s6, s3
	s_addc_u32 s57, s85, 0
	s_sub_i32 s6, 0x1f00, s6
	s_sub_i32 s7, s6, s3
	s_cmp_ge_u32 s6, s3
	s_cselect_b32 s6, s7, s6
	s_sub_i32 s7, s6, s3
	s_cmp_ge_u32 s6, s3
	s_cselect_b32 s6, s7, s6
	s_sub_i32 s6, s34, s6
	s_ashr_i32 s7, s6, 31
	s_abs_i32 s6, s6
	s_mul_hi_u32 s8, s6, s35
	s_mul_i32 s8, s8, s3
	s_sub_i32 s6, s6, s8
	s_sub_i32 s8, s6, s3
	s_cmp_ge_u32 s6, s3
	s_cselect_b32 s6, s8, s6
	s_sub_i32 s8, s6, s3
	s_cmp_ge_u32 s6, s3
	s_cselect_b32 s3, s8, s6
	s_xor_b32 s3, s3, s7
	s_sub_i32 s3, s3, s7
	v_writelane_b32 v192, s18, 35
	v_mov_b32_e32 v14, v174
	s_cmpk_gt_i32 s3, 0x3ff
	v_writelane_b32 v192, s19, 36
	s_cbranch_scc1 .LBB0_127
	s_cmpk_lg_i32 s86, 0x100
	s_cbranch_scc1 .Lcv3_orig
	s_load_dwordx2 s[6:7], s[0:1], 0x68
	v_lshrrev_b32_e32 v2, 6, v174
	v_and_b32_e32 v1, 63, v174
	v_lshrrev_b32_e32 v6, 3, v174
	v_readfirstlane_b32 s8, v2
	v_and_b32_e32 v7, 7, v174
	s_mul_i32 s9, s8, 0x1000
	v_lshlrev_b32_e32 v18, 2, v1
	v_add_u32_e32 v18, s9, v18
	s_mul_i32 s11, s8, 260
	v_mul_u32_u24_e32 v8, 0x820, v7
	v_lshl_add_u32 v8, v6, 2, v8
	v_mov_b32_e32 v9, 0x2080
	v_mul_u32_u24_e32 v9, v9, v6
	v_lshl_add_u32 v9, v7, 4, v9
	s_add_u32 s12, s84, 0x27f8000
	s_addc_u32 s13, s85, 0
	s_mov_b32 s15, 0
	s_waitcnt lgkmcnt(0)
	s_add_u32 s6, s6, 0x1000000
	s_addc_u32 s7, s7, 0
	v_mov_b32_e32 v19, 0
	v_lshl_add_u64 v[10:11], s[6:7], 0, v[18:19]
	s_mov_b32 s16, 0x8000
	s_mov_b32 s17, 0
	s_add_i32 s14, s3, 0x0
	s_lshr_b32 s9, s14, 4
	s_and_b32 vcc_lo, s14, 0xf
	s_mul_i32 s14, s9, 0x40000
	s_lshl_b32 vcc_lo, vcc_lo, 8
	s_add_i32 s14, s14, vcc_lo
	v_lshl_add_u64 v[12:13], v[10:11], 0, s[14:15]
	s_add_i32 m0, s11, 0x0
	s_nop 0
	global_load_lds_dword v[12:13], off
	v_lshl_add_u64 v[12:13], v[12:13], 0, s[16:17]
	s_add_i32 m0, s11, 0x820
	s_nop 0
	global_load_lds_dword v[12:13], off
	v_lshl_add_u64 v[12:13], v[12:13], 0, s[16:17]
	s_add_i32 m0, s11, 0x1040
	s_nop 0
	global_load_lds_dword v[12:13], off
	v_lshl_add_u64 v[12:13], v[12:13], 0, s[16:17]
	s_add_i32 m0, s11, 0x1860
	s_nop 0
	global_load_lds_dword v[12:13], off
	v_lshl_add_u64 v[12:13], v[12:13], 0, s[16:17]
	s_add_i32 m0, s11, 0x2080
	s_nop 0
	global_load_lds_dword v[12:13], off
	v_lshl_add_u64 v[12:13], v[12:13], 0, s[16:17]
	s_add_i32 m0, s11, 0x28a0
	s_nop 0
	global_load_lds_dword v[12:13], off
	v_lshl_add_u64 v[12:13], v[12:13], 0, s[16:17]
	s_add_i32 m0, s11, 0x30c0
	s_nop 0
	global_load_lds_dword v[12:13], off
	v_lshl_add_u64 v[12:13], v[12:13], 0, s[16:17]
	s_add_i32 m0, s11, 0x38e0
	s_nop 0
	global_load_lds_dword v[12:13], off
	s_add_i32 s14, s3, 0x100
	s_lshr_b32 s9, s14, 4
	s_and_b32 vcc_lo, s14, 0xf
	s_mul_i32 s14, s9, 0x40000
	s_lshl_b32 vcc_lo, vcc_lo, 8
	s_add_i32 s14, s14, vcc_lo
	v_lshl_add_u64 v[12:13], v[10:11], 0, s[14:15]
	s_add_i32 m0, s11, 0x4100
	s_nop 0
	global_load_lds_dword v[12:13], off
	v_lshl_add_u64 v[12:13], v[12:13], 0, s[16:17]
	s_add_i32 m0, s11, 0x4920
	s_nop 0
	global_load_lds_dword v[12:13], off
	v_lshl_add_u64 v[12:13], v[12:13], 0, s[16:17]
	s_add_i32 m0, s11, 0x5140
	s_nop 0
	global_load_lds_dword v[12:13], off
	v_lshl_add_u64 v[12:13], v[12:13], 0, s[16:17]
	s_add_i32 m0, s11, 0x5960
	s_nop 0
	global_load_lds_dword v[12:13], off
	v_lshl_add_u64 v[12:13], v[12:13], 0, s[16:17]
	s_add_i32 m0, s11, 0x6180
	s_nop 0
	global_load_lds_dword v[12:13], off
	v_lshl_add_u64 v[12:13], v[12:13], 0, s[16:17]
	s_add_i32 m0, s11, 0x69a0
	s_nop 0
	global_load_lds_dword v[12:13], off
	v_lshl_add_u64 v[12:13], v[12:13], 0, s[16:17]
	s_add_i32 m0, s11, 0x71c0
	s_nop 0
	global_load_lds_dword v[12:13], off
	v_lshl_add_u64 v[12:13], v[12:13], 0, s[16:17]
	s_add_i32 m0, s11, 0x79e0
	s_nop 0
	global_load_lds_dword v[12:13], off
	s_waitcnt vmcnt(8)
	s_barrier
	s_add_i32 s14, s3, 0x200
	s_lshr_b32 s9, s14, 4
	s_and_b32 vcc_lo, s14, 0xf
	s_mul_i32 s14, s9, 0x40000
	s_lshl_b32 vcc_lo, vcc_lo, 8
	s_add_i32 s14, s14, vcc_lo
	v_lshl_add_u64 v[12:13], v[10:11], 0, s[14:15]
	s_add_i32 m0, s11, 0x8200
	s_nop 0
	global_load_lds_dword v[12:13], off
	v_lshl_add_u64 v[12:13], v[12:13], 0, s[16:17]
	s_add_i32 m0, s11, 0x8a20
	s_nop 0
	global_load_lds_dword v[12:13], off
	v_lshl_add_u64 v[12:13], v[12:13], 0, s[16:17]
	s_add_i32 m0, s11, 0x9240
	s_nop 0
	global_load_lds_dword v[12:13], off
	v_lshl_add_u64 v[12:13], v[12:13], 0, s[16:17]
	s_add_i32 m0, s11, 0x9a60
	s_nop 0
	global_load_lds_dword v[12:13], off
	v_lshl_add_u64 v[12:13], v[12:13], 0, s[16:17]
	s_add_i32 m0, s11, 0xa280
	s_nop 0
	global_load_lds_dword v[12:13], off
	v_lshl_add_u64 v[12:13], v[12:13], 0, s[16:17]
	s_add_i32 m0, s11, 0xaaa0
	s_nop 0
	global_load_lds_dword v[12:13], off
	v_lshl_add_u64 v[12:13], v[12:13], 0, s[16:17]
	s_add_i32 m0, s11, 0xb2c0
	s_nop 0
	global_load_lds_dword v[12:13], off
	v_lshl_add_u64 v[12:13], v[12:13], 0, s[16:17]
	s_add_i32 m0, s11, 0xbae0
	s_nop 0
	global_load_lds_dword v[12:13], off
	v_mov_b32_e32 v14, v8
	v_add_u32_e32 v15, 0x410, v14
	ds_read2_b32 v[20:21], v14 offset1:65
	ds_read2_b32 v[22:23], v14 offset0:130 offset1:195
	ds_read2_b32 v[24:25], v15 offset1:65
	ds_read2_b32 v[26:27], v15 offset0:130 offset1:195
	s_add_i32 s14, s3, 0x0
	s_lshr_b32 s9, s14, 4
	s_and_b32 vcc_lo, s14, 0xf
	s_mul_i32 vcc_lo, vcc_lo, 0x82000
	s_lshl_b32 s9, s9, 7
	s_add_i32 vcc_lo, vcc_lo, s9
	v_add_u32_e32 v16, vcc_lo, v9
	s_waitcnt lgkmcnt(0)
	v_cvt_pk_bf16_f32 v28, v20, v21
	v_cvt_pk_bf16_f32 v29, v22, v23
	v_cvt_pk_bf16_f32 v30, v24, v25
	v_cvt_pk_bf16_f32 v31, v26, v27
	global_store_dwordx4 v16, v[28:31], s[12:13]
	s_waitcnt vmcnt(9)
	s_barrier
	s_add_i32 s14, s3, 0x300
	s_lshr_b32 s9, s14, 4
	s_and_b32 vcc_lo, s14, 0xf
	s_mul_i32 s14, s9, 0x40000
	s_lshl_b32 vcc_lo, vcc_lo, 8
	s_add_i32 s14, s14, vcc_lo
	v_lshl_add_u64 v[12:13], v[10:11], 0, s[14:15]
	s_add_i32 m0, s11, 0x0
	s_nop 0
	global_load_lds_dword v[12:13], off
	v_lshl_add_u64 v[12:13], v[12:13], 0, s[16:17]
	s_add_i32 m0, s11, 0x820
	s_nop 0
	global_load_lds_dword v[12:13], off
	v_lshl_add_u64 v[12:13], v[12:13], 0, s[16:17]
	s_add_i32 m0, s11, 0x1040
	s_nop 0
	global_load_lds_dword v[12:13], off
	v_lshl_add_u64 v[12:13], v[12:13], 0, s[16:17]
	s_add_i32 m0, s11, 0x1860
	s_nop 0
	global_load_lds_dword v[12:13], off
	v_lshl_add_u64 v[12:13], v[12:13], 0, s[16:17]
	s_add_i32 m0, s11, 0x2080
	s_nop 0
	global_load_lds_dword v[12:13], off
	v_lshl_add_u64 v[12:13], v[12:13], 0, s[16:17]
	s_add_i32 m0, s11, 0x28a0
	s_nop 0
	global_load_lds_dword v[12:13], off
	v_lshl_add_u64 v[12:13], v[12:13], 0, s[16:17]
	s_add_i32 m0, s11, 0x30c0
	s_nop 0
	global_load_lds_dword v[12:13], off
	v_lshl_add_u64 v[12:13], v[12:13], 0, s[16:17]
	s_add_i32 m0, s11, 0x38e0
	s_nop 0
	global_load_lds_dword v[12:13], off
	v_add_u32_e32 v14, 0x4100, v8
	v_add_u32_e32 v15, 0x410, v14
	ds_read2_b32 v[20:21], v14 offset1:65
	ds_read2_b32 v[22:23], v14 offset0:130 offset1:195
	ds_read2_b32 v[24:25], v15 offset1:65
	ds_read2_b32 v[26:27], v15 offset0:130 offset1:195
	s_add_i32 s14, s3, 0x100
	s_lshr_b32 s9, s14, 4
	s_and_b32 vcc_lo, s14, 0xf
	s_mul_i32 vcc_lo, vcc_lo, 0x82000
	s_lshl_b32 s9, s9, 7
	s_add_i32 vcc_lo, vcc_lo, s9
	v_add_u32_e32 v16, vcc_lo, v9
	s_waitcnt lgkmcnt(0)
	v_cvt_pk_bf16_f32 v28, v20, v21
	v_cvt_pk_bf16_f32 v29, v22, v23
	v_cvt_pk_bf16_f32 v30, v24, v25
	v_cvt_pk_bf16_f32 v31, v26, v27
	global_store_dwordx4 v16, v[28:31], s[12:13]
	s_waitcnt vmcnt(10)
	s_barrier
	v_add_u32_e32 v14, 0x8200, v8
	v_add_u32_e32 v15, 0x410, v14
	ds_read2_b32 v[20:21], v14 offset1:65
	ds_read2_b32 v[22:23], v14 offset0:130 offset1:195
	ds_read2_b32 v[24:25], v15 offset1:65
	ds_read2_b32 v[26:27], v15 offset0:130 offset1:195
	s_add_i32 s14, s3, 0x200
	s_lshr_b32 s9, s14, 4
	s_and_b32 vcc_lo, s14, 0xf
	s_mul_i32 vcc_lo, vcc_lo, 0x82000
	s_lshl_b32 s9, s9, 7
	s_add_i32 vcc_lo, vcc_lo, s9
	v_add_u32_e32 v16, vcc_lo, v9
	s_waitcnt lgkmcnt(0)
	v_cvt_pk_bf16_f32 v28, v20, v21
	v_cvt_pk_bf16_f32 v29, v22, v23
	v_cvt_pk_bf16_f32 v30, v24, v25
	v_cvt_pk_bf16_f32 v31, v26, v27
	global_store_dwordx4 v16, v[28:31], s[12:13]
	s_waitcnt vmcnt(2)
	s_barrier
	v_mov_b32_e32 v14, v8
	v_add_u32_e32 v15, 0x410, v14
	ds_read2_b32 v[20:21], v14 offset1:65
	ds_read2_b32 v[22:23], v14 offset0:130 offset1:195
	ds_read2_b32 v[24:25], v15 offset1:65
	ds_read2_b32 v[26:27], v15 offset0:130 offset1:195
	s_add_i32 s14, s3, 0x300
	s_lshr_b32 s9, s14, 4
	s_and_b32 vcc_lo, s14, 0xf
	s_mul_i32 vcc_lo, vcc_lo, 0x82000
	s_lshl_b32 s9, s9, 7
	s_add_i32 vcc_lo, vcc_lo, s9
	v_add_u32_e32 v16, vcc_lo, v9
	s_waitcnt lgkmcnt(0)
	v_cvt_pk_bf16_f32 v28, v20, v21
	v_cvt_pk_bf16_f32 v29, v22, v23
	v_cvt_pk_bf16_f32 v30, v24, v25
	v_cvt_pk_bf16_f32 v31, v26, v27
	global_store_dwordx4 v16, v[28:31], s[12:13]
	s_barrier
	s_branch .LBB0_127
.Lcv3_orig:
	s_load_dwordx16 s[40:55], s[0:1], 0x40
	v_lshlrev_b32_e32 v1, 2, v14
	v_and_b32_e32 v2, 0xfc, v1
	v_ashrrev_i32_e32 v1, 6, v14
	v_mov_b32_e32 v3, 0
	s_waitcnt lgkmcnt(0)
	s_add_u32 s6, s50, 0x1000000
	s_addc_u32 s7, s51, 0
	s_ashr_i32 s8, s3, 31
	s_lshr_b32 s8, s8, 28
	s_add_i32 s8, s3, s8
	s_lshl_b32 s9, s8, 2
	s_and_b32 s8, s8, 0x3fffff0
	s_sub_i32 s8, s3, s8
	s_lshl_b32 s8, s8, 6
	s_and_b32 s10, s9, 0xffffffc0
	s_ashr_i32 s9, s8, 31
	s_lshl_b64 s[8:9], s[8:9], 2
	s_add_u32 s8, s6, s8
	v_add_u32_e32 v6, s10, v1
	s_addc_u32 s9, s7, s9
	v_ashrrev_i32_e32 v7, 31, v6
	v_lshl_add_u64 v[4:5], s[8:9], 0, v[2:3]
	v_lshlrev_b64 v[6:7], 12, v[6:7]
	v_lshl_add_u64 v[16:17], v[4:5], 0, v[6:7]
	v_add_u32_e32 v6, 0x200, v14
	v_ashrrev_i32_e32 v6, 6, v6
	v_add_u32_e32 v8, s10, v6
	v_ashrrev_i32_e32 v9, 31, v8
	v_add_u32_e32 v7, 0x400, v14
	v_lshlrev_b64 v[8:9], 12, v[8:9]
	v_ashrrev_i32_e32 v7, 6, v7
	v_lshl_add_u64 v[18:19], v[4:5], 0, v[8:9]
	v_add_u32_e32 v8, s10, v7
	v_ashrrev_i32_e32 v9, 31, v8
	v_lshlrev_b64 v[8:9], 12, v[8:9]
	v_lshl_add_u64 v[20:21], v[4:5], 0, v[8:9]
	v_add_u32_e32 v8, 0x600, v14
	v_ashrrev_i32_e32 v8, 6, v8
	v_add_u32_e32 v10, s10, v8
	v_ashrrev_i32_e32 v11, 31, v10
	v_add_u32_e32 v9, 0x800, v14
	v_lshlrev_b64 v[10:11], 12, v[10:11]
	v_ashrrev_i32_e32 v9, 6, v9
	s_waitcnt vmcnt(3)
	v_lshl_add_u64 v[26:27], v[4:5], 0, v[10:11]
	v_add_u32_e32 v10, s10, v9
	v_ashrrev_i32_e32 v11, 31, v10
	v_lshlrev_b64 v[10:11], 12, v[10:11]
	s_waitcnt vmcnt(1)
	v_lshl_add_u64 v[28:29], v[4:5], 0, v[10:11]
	v_add_u32_e32 v10, 0xa00, v14
	v_ashrrev_i32_e32 v10, 6, v10
	v_add_u32_e32 v12, s10, v10
	v_ashrrev_i32_e32 v13, 31, v12
	v_add_u32_e32 v11, 0xc00, v14
	v_lshlrev_b64 v[12:13], 12, v[12:13]
	v_ashrrev_i32_e32 v11, 6, v11
	v_lshl_add_u64 v[30:31], v[4:5], 0, v[12:13]
	v_add_u32_e32 v12, s10, v11
	v_ashrrev_i32_e32 v13, 31, v12
	v_lshlrev_b64 v[12:13], 12, v[12:13]
	v_lshl_add_u64 v[32:33], v[4:5], 0, v[12:13]
	v_add_u32_e32 v12, 0xe00, v14
	v_ashrrev_i32_e32 v12, 6, v12
	v_add_u32_e32 v22, s10, v12
	v_ashrrev_i32_e32 v23, 31, v22
	v_lshlrev_b64 v[22:23], 12, v[22:23]
	v_lshl_add_u64 v[4:5], v[4:5], 0, v[22:23]
	global_load_dword v23, v[16:17], off
	global_load_dword v24, v[18:19], off
	global_load_dword v25, v[20:21], off
	s_nop 0
	global_load_dword v26, v[26:27], off
	s_nop 0
	global_load_dword v27, v[28:29], off
	s_nop 0
	global_load_dword v28, v[30:31], off
	global_load_dword v29, v[32:33], off
	s_nop 0
	global_load_dword v30, v[4:5], off
	v_add_u32_e32 v21, 0, v2
	v_lshl_add_u64 v[4:5], s[6:7], 0, v[2:3]
	v_lshlrev_b32_e32 v2, 3, v14
	v_ashrrev_i32_e32 v13, 3, v14
	v_and_b32_e32 v2, 56, v2
	s_movk_i32 s6, 0x104
	v_lshl_add_u32 v22, v13, 2, 0
	v_mul_u32_u24_e32 v31, 0x104, v2
	v_mul_lo_u32 v14, v1, s6
	v_mul_lo_u32 v15, v6, s6
	v_mul_lo_u32 v16, v7, s6
	v_mul_lo_u32 v17, v8, s6
	v_mul_lo_u32 v18, v9, s6
	v_mul_lo_u32 v19, v10, s6
	v_mul_lo_u32 v20, v11, s6
	v_mul_lo_u32 v32, v12, s6
	s_lshl_b32 s12, s3, 6
	s_lshl_b32 s10, s86, 6
	v_add_u32_e32 v14, v21, v14
	v_add_u32_e32 v15, v21, v15
	v_add_u32_e32 v16, v21, v16
	v_add_u32_e32 v17, v21, v17
	v_add_u32_e32 v18, v21, v18
	v_add_u32_e32 v19, v21, v19
	v_add_u32_e32 v20, v21, v20
	v_add_u32_e32 v21, v21, v32
	v_add_u32_e32 v22, v22, v31
	s_movk_i32 s11, 0x2080
	v_lshlrev_b32_e32 v2, 1, v2
	s_branch .LBB0_123
